# PEER combine (three of four layers): id-dependent scale gathers issued right after the id pair arrives, one dependent round trip fewer per iteration
# baseline (speedup 1.0000x reference)
.LBB0_1139:
	v_lshl_add_u64 v[12:13], s[30:31], 0, v[8:9]
	v_add_co_u32_e32 v12, vcc, 0x2ade6000, v12
	v_lshl_add_u64 v[16:17], s[30:31], 0, v[10:11]
	s_nop 0
	v_addc_co_u32_e32 v13, vcc, 0, v13, vcc
	global_load_dwordx2 v[14:15], v[12:13], off
	v_lshl_add_u64 v[12:13], s[30:31], 0, v[4:5]
	v_add_co_u32_e32 v20, vcc, 0x40d86000, v12
	s_nop 1
	v_addc_co_u32_e32 v21, vcc, 0, v13, vcc
	v_add_co_u32_e32 v22, vcc, 0x41206000, v12
	s_nop 1
	v_addc_co_u32_e32 v23, vcc, 0, v13, vcc
	v_add_co_u32_e32 v26, vcc, 0x41686000, v12
	s_nop 1
	v_addc_co_u32_e32 v27, vcc, 0, v13, vcc
	v_add_co_u32_e32 v28, vcc, 0x41b06000, v12
	s_nop 1
	v_addc_co_u32_e32 v29, vcc, 0, v13, vcc
	v_add_co_u32_e32 v32, vcc, 0x41f86000, v12
	global_load_dword v24, v[22:23], off
	s_nop 0
	global_load_dword v23, v[28:29], off
	v_addc_co_u32_e32 v33, vcc, 0, v13, vcc
	v_add_co_u32_e32 v34, vcc, 0x42406000, v12
	s_waitcnt vmcnt(0)
	v_ashrrev_i32_e32 v49, 31, v14
	v_mov_b32_e32 v48, v14
	v_lshl_add_u64 v[50:51], v[48:49], 2, s[8:9]
	v_ashrrev_i32_e32 v41, 31, v15
	v_mov_b32_e32 v40, v15
	v_lshl_add_u64 v[40:41], v[40:41], 2, s[8:9]
	s_mov_b64 s[98:99], 0x10000
	global_load_dword v14, v[50:51], off
	global_load_dword v44, v[40:41], off
	v_lshl_add_u64 v[42:43], v[50:51], 0, s[98:99]
	global_load_dword v45, v[42:43], off
	v_lshl_add_u64 v[42:43], v[40:41], 0, s[98:99]
	global_load_dword v46, v[42:43], off
	v_cvt_f32_f16_e32 v31, v23
	v_addc_co_u32_e32 v35, vcc, 0, v13, vcc
	v_add_co_u32_e32 v36, vcc, 0x42886000, v12
	s_nop 1
	v_addc_co_u32_e32 v37, vcc, 0, v13, vcc
	global_load_dword v30, v[20:21], off
	global_load_dword v29, v[26:27], off
	s_nop 0
	global_load_dword v26, v[32:33], off
	global_load_dword v25, v[36:37], off
	v_add_co_u32_e32 v12, vcc, 0x42d06000, v12
	s_waitcnt vmcnt(2)
	v_cvt_f32_f16_e32 v22, v29
	v_addc_co_u32_e32 v13, vcc, 0, v13, vcc
	global_load_dword v28, v[34:35], off
	global_load_dword v27, v[12:13], off
	v_add_co_u32_e32 v20, vcc, 0x2b6e6000, v16
	s_nop 1
	v_addc_co_u32_e32 v21, vcc, 0, v17, vcc
	global_load_dwordx2 v[12:13], v[20:21], off
	v_cvt_f32_f16_e32 v20, v30
	v_cvt_f32_f16_e32 v21, v24
	v_add_f32_e32 v20, 0, v20
	v_add_f32_e32 v20, v20, v21
	s_waitcnt vmcnt(1)
	v_cvt_f32_f16_e32 v21, v26
	v_add_f32_e32 v20, v20, v22
	v_add_f32_e32 v20, v20, v31
	s_waitcnt vmcnt(1)
	v_cvt_f32_f16_e32 v31, v25
	v_add_f32_e32 v20, v20, v21
	s_waitcnt vmcnt(1)
	v_cvt_f32_f16_e32 v22, v28
	s_waitcnt vmcnt(1)
	v_cvt_f32_f16_e32 v32, v27
	v_add_f32_e32 v20, v20, v22
	v_add_f32_e32 v20, v20, v31
	v_add_f32_e32 v20, v20, v32
	s_waitcnt vmcnt(0)
	v_mul_f32_e32 v20, v20, v14
	v_mul_f32_e32 v21, 0x3f3504f3, v20
	v_cmp_nlt_f32_e64 s[14:15], |v21|, 1.0
	s_and_saveexec_b64 s[26:27], s[14:15]
	s_xor_b64 s[14:15], exec, s[26:27]
	s_cbranch_execz .LBB0_1141
	v_fma_f32 v14, |v21|, s2, v18
	v_fma_f32 v14, |v21|, v14, s16
	v_fma_f32 v14, |v21|, v14, s17
	v_fma_f32 v14, |v21|, v14, s18
	v_fma_f32 v14, |v21|, v14, s19
	v_fma_f32 v14, |v21|, v14, s20
	v_fma_f32 v14, |v21|, v14, |v21|
	v_mul_f32_e32 v22, 0xbfb8aa3b, v14
	v_fma_f32 v31, v14, s21, -v22
	v_rndne_f32_e32 v32, v22
	v_fmac_f32_e32 v31, 0xb2a5705f, v14
	v_sub_f32_e32 v22, v22, v32
	v_add_f32_e32 v22, v22, v31
	v_cvt_i32_f32_e32 v31, v32
	v_exp_f32_e32 v22, v22
	v_cmp_nlt_f32_e32 vcc, s22, v14
	v_ldexp_f32 v22, v22, v31
	s_nop 0
	v_cndmask_b32_e32 v22, 0, v22, vcc
	v_cmp_ngt_f32_e32 vcc, s23, v14
	s_nop 1
	v_cndmask_b32_e32 v14, v19, v22, vcc
	v_sub_f32_e32 v22, 1.0, v14

.LBB0_3038:
	v_lshl_add_u64 v[12:13], s[30:31], 0, v[8:9]
	v_add_co_u32_e32 v12, vcc, 0x2ade6000, v12
	v_lshl_add_u64 v[16:17], s[30:31], 0, v[10:11]
	s_nop 0
	v_addc_co_u32_e32 v13, vcc, 0, v13, vcc
	global_load_dwordx2 v[14:15], v[12:13], off
	v_lshl_add_u64 v[12:13], s[30:31], 0, v[4:5]
	v_add_co_u32_e32 v20, vcc, 0x40d86000, v12
	s_nop 1
	v_addc_co_u32_e32 v21, vcc, 0, v13, vcc
	v_add_co_u32_e32 v22, vcc, 0x41206000, v12
	s_nop 1
	v_addc_co_u32_e32 v23, vcc, 0, v13, vcc
	v_add_co_u32_e32 v26, vcc, 0x41686000, v12
	s_nop 1
	v_addc_co_u32_e32 v27, vcc, 0, v13, vcc
	v_add_co_u32_e32 v28, vcc, 0x41b06000, v12
	s_nop 1
	v_addc_co_u32_e32 v29, vcc, 0, v13, vcc
	v_add_co_u32_e32 v32, vcc, 0x41f86000, v12
	global_load_dword v24, v[22:23], off
	s_nop 0
	global_load_dword v23, v[28:29], off
	v_addc_co_u32_e32 v33, vcc, 0, v13, vcc
	v_add_co_u32_e32 v34, vcc, 0x42406000, v12
	s_waitcnt vmcnt(0)
	v_ashrrev_i32_e32 v49, 31, v14
	v_mov_b32_e32 v48, v14
	v_lshl_add_u64 v[50:51], v[48:49], 2, s[10:11]
	v_ashrrev_i32_e32 v41, 31, v15
	v_mov_b32_e32 v40, v15
	v_lshl_add_u64 v[40:41], v[40:41], 2, s[10:11]
	s_mov_b64 s[98:99], 0x10000
	global_load_dword v14, v[50:51], off
	global_load_dword v44, v[40:41], off
	v_lshl_add_u64 v[42:43], v[50:51], 0, s[98:99]
	global_load_dword v45, v[42:43], off
	v_lshl_add_u64 v[42:43], v[40:41], 0, s[98:99]
	global_load_dword v46, v[42:43], off
	v_cvt_f32_f16_e32 v31, v23
	v_addc_co_u32_e32 v35, vcc, 0, v13, vcc
	v_add_co_u32_e32 v36, vcc, 0x42886000, v12
	s_nop 1
	v_addc_co_u32_e32 v37, vcc, 0, v13, vcc
	global_load_dword v30, v[20:21], off
	global_load_dword v29, v[26:27], off
	s_nop 0
	global_load_dword v26, v[32:33], off
	global_load_dword v25, v[36:37], off
	v_add_co_u32_e32 v12, vcc, 0x42d06000, v12
	s_waitcnt vmcnt(2)
	v_cvt_f32_f16_e32 v22, v29
	v_addc_co_u32_e32 v13, vcc, 0, v13, vcc
	global_load_dword v28, v[34:35], off
	global_load_dword v27, v[12:13], off
	v_add_co_u32_e32 v20, vcc, 0x2b6e6000, v16
	s_nop 1
	v_addc_co_u32_e32 v21, vcc, 0, v17, vcc
	global_load_dwordx2 v[12:13], v[20:21], off
	v_cvt_f32_f16_e32 v20, v30
	v_cvt_f32_f16_e32 v21, v24
	v_add_f32_e32 v20, 0, v20
	v_add_f32_e32 v20, v20, v21
	s_waitcnt vmcnt(1)
	v_cvt_f32_f16_e32 v21, v26
	v_add_f32_e32 v20, v20, v22
	v_add_f32_e32 v20, v20, v31
	s_waitcnt vmcnt(1)
	v_cvt_f32_f16_e32 v31, v25
	v_add_f32_e32 v20, v20, v21
	s_waitcnt vmcnt(1)
	v_cvt_f32_f16_e32 v22, v28
	s_waitcnt vmcnt(1)
	v_cvt_f32_f16_e32 v32, v27
	v_add_f32_e32 v20, v20, v22
	v_add_f32_e32 v20, v20, v31
	v_add_f32_e32 v20, v20, v32
	s_waitcnt vmcnt(0)
	v_mul_f32_e32 v20, v20, v14
	v_mul_f32_e32 v21, 0x3f3504f3, v20
	v_cmp_nlt_f32_e64 s[16:17], |v21|, 1.0
	s_and_saveexec_b64 s[28:29], s[16:17]
	s_xor_b64 s[16:17], exec, s[28:29]
	s_cbranch_execz .LBB0_3040
	v_fma_f32 v14, |v21|, s2, v18
	v_fma_f32 v14, |v21|, v14, s18
	v_fma_f32 v14, |v21|, v14, s19
	v_fma_f32 v14, |v21|, v14, s20
	v_fma_f32 v14, |v21|, v14, s21
	v_fma_f32 v14, |v21|, v14, s22
	v_fma_f32 v14, |v21|, v14, |v21|
	v_mul_f32_e32 v22, 0xbfb8aa3b, v14
	v_fma_f32 v31, v14, s23, -v22
	v_rndne_f32_e32 v32, v22
	v_fmac_f32_e32 v31, 0xb2a5705f, v14
	v_sub_f32_e32 v22, v22, v32
	v_add_f32_e32 v22, v22, v31
	v_cvt_i32_f32_e32 v31, v32
	v_exp_f32_e32 v22, v22
	v_cmp_nlt_f32_e32 vcc, s24, v14
	v_ldexp_f32 v22, v22, v31
	s_nop 0
	v_cndmask_b32_e32 v22, 0, v22, vcc
	v_cmp_ngt_f32_e32 vcc, s25, v14
	s_nop 1
	v_cndmask_b32_e32 v14, v19, v22, vcc
	v_sub_f32_e32 v22, 1.0, v14
